# final-norm loop: second half-row xb and gain loads hoisted to loop top (one wait per row)
# baseline (speedup 1.0000x reference)
; __global__ void __launch_bounds__(NTHREADS) fwd_megakernel(Params P) {
;     ...
;                 for (int row = gw; row < RC; row += NGW) { const float rs = __builtin_amdgcn_rsqf(pq[row] * (1.f / DM) + EPS);
; #pragma unroll
;                     for (int hf = 0; hf < 2; ++hf) { const u32x4 r = __builtin_nontemporal_load((const u32x4*)(xp + (size_t)row * DM + hf * 512 + lane * 8));
;                         const f32x4 g0 = *(const f32x4*)(gf + hf * 512 + lane * 8), g1 = *(const f32x4*)(gf + hf * 512 + lane * 8 + 4);
;                         f32x4 y0, y1;
;                         y0[0] = __builtin_bit_cast(float, r.x << 16); y0[1] = __builtin_bit_cast(float, r.x & 0xffff0000u); y0[2] = __builtin_bit_cast(float, r.y << 16); y0[3] = __builtin_bit_cast(float, r.y & 0xffff0000u);
;                         y1[0] = __builtin_bit_cast(float, r.z << 16); y1[1] = __builtin_bit_cast(float, r.z & 0xffff0000u); y1[2] = __builtin_bit_cast(float, r.w << 16); y1[3] = __builtin_bit_cast(float, r.w & 0xffff0000u);
;                         f32x4* op = (f32x4*)(po + (size_t)row * DM + hf * 512 + lane * 8);
;                         __builtin_nontemporal_store(y0 * rs * g0, op); __builtin_nontemporal_store(y1 * rs * g1, op + 1); } }
.LBB0_389:
	global_load_dword v0, v1, s[0:1]
	global_load_dwordx4 v[8:11], v[4:5], off offset:-1024 nt
	global_load_dwordx4 v[12:15], v[2:3], off
	global_load_dwordx4 v[16:19], v[2:3], off offset:16
	global_load_dwordx4 v[100:103], v[4:5], off nt
	global_load_dwordx4 v[104:107], v[2:3], off offset:2048
	global_load_dwordx4 v[108:111], v[2:3], off offset:2064
	s_add_i32 s2, s2, s18
	s_add_u32 s0, s0, s10
	s_addc_u32 s1, s1, s11
	s_cmp_lt_i32 s2, 0x10000
	s_waitcnt vmcnt(0)
	v_fmamk_f32 v0, v0, 0x3a800000, v222
	v_rsq_f32_e32 v0, v0
	v_lshlrev_b32_e32 v20, 16, v8
	v_and_b32_e32 v21, 0xffff0000, v8
	v_lshlrev_b32_e32 v8, 16, v9
	v_and_b32_e32 v9, 0xffff0000, v9
	v_lshlrev_b32_e32 v22, 16, v10
	v_and_b32_e32 v23, 0xffff0000, v10
	v_lshlrev_b32_e32 v10, 16, v11
	v_and_b32_e32 v11, 0xffff0000, v11
	v_pk_mul_f32 v[20:21], v[0:1], v[20:21] op_sel_hi:[0,1]
	v_pk_mul_f32 v[8:9], v[0:1], v[8:9] op_sel_hi:[0,1]
	v_pk_mul_f32 v[22:23], v[0:1], v[22:23] op_sel_hi:[0,1]
	v_pk_mul_f32 v[24:25], v[0:1], v[10:11] op_sel_hi:[0,1]
	v_pk_mul_f32 v[10:11], v[14:15], v[8:9]
	v_pk_mul_f32 v[8:9], v[12:13], v[20:21]
	v_pk_mul_f32 v[14:15], v[18:19], v[24:25]
	v_pk_mul_f32 v[12:13], v[16:17], v[22:23]
	global_store_dwordx4 v[6:7], v[8:11], off offset:-2064 nt
	global_store_dwordx4 v[6:7], v[12:15], off offset:-2048 nt
	v_lshl_add_u64 v[4:5], v[4:5], 0, s[12:13]
	v_lshlrev_b32_e32 v20, 16, v100
	v_and_b32_e32 v21, 0xffff0000, v100
	v_lshlrev_b32_e32 v8, 16, v101
	v_and_b32_e32 v9, 0xffff0000, v101
	v_lshlrev_b32_e32 v22, 16, v102
	v_and_b32_e32 v23, 0xffff0000, v102
	v_lshlrev_b32_e32 v10, 16, v103
	v_and_b32_e32 v11, 0xffff0000, v103
	v_pk_mul_f32 v[20:21], v[0:1], v[20:21] op_sel_hi:[0,1]
	v_pk_mul_f32 v[8:9], v[0:1], v[8:9] op_sel_hi:[0,1]
	v_pk_mul_f32 v[22:23], v[0:1], v[22:23] op_sel_hi:[0,1]
	v_pk_mul_f32 v[24:25], v[0:1], v[10:11] op_sel_hi:[0,1]
	v_pk_mul_f32 v[10:11], v[106:107], v[8:9]
	v_pk_mul_f32 v[8:9], v[104:105], v[20:21]
	v_pk_mul_f32 v[14:15], v[110:111], v[24:25]
	v_pk_mul_f32 v[12:13], v[108:109], v[22:23]
	global_store_dwordx4 v[6:7], v[8:11], off offset:-16 nt
	global_store_dwordx4 v[6:7], v[12:15], off nt
	v_lshl_add_u64 v[6:7], v[6:7], 0, s[16:17]
	s_cbranch_scc1 .LBB0_389
	v_writelane_b32 v255, s18, 11
	s_nop 1
	v_writelane_b32 v255, s19, 12
